# HGRN2 scan: rows 1..3 of each thread's next-tile loads derived from row 0 by +-1 row pitch (3 scalar adds instead of 18-op scalar row computation each)
# speedup vs baseline: 1.0173x; 1.0055x over previous
; __device__ __forceinline__ float sigmoid_(float x) { return __builtin_amdgcn_rcpf(1.f + __expf(-x)); }
; __device__ __forceinline__ int tid_() { int t = threadIdx.x; asm volatile("" : "+v"(t)); return t; }
; __device__ __forceinline__ void scan_hgrn_mfma(const Params& P, unsigned char* LB, int l, int c) {
;     using CL = ChunkLds<128, 64>;
;     const int tid = tid_(), lane = tid & 63, wave = __builtin_amdgcn_readfirstlane(tid >> 6), fr = lane & 15, fq = lane >> 4;
;     const int vq = c & 1, b = c >> 4, h = (c >> 2) & 3, d = (c >> 1) & 1;
;     const float* U = (const float*)(P.ws + WS_U); bf16* YD = (bf16*)(P.ws + WS_YD);
;     unsigned char* OP = LB;
;     float* tot = (float*)(LB + 58368);
;     const int k = 2 * lane, qt = wave & 3, cb = wave >> 2;
;     const int vv_ = tid & 63, vqt = wave & 3, vc = wave >> 2;
;     f32x2 lb2 = {0.f, 0.f};
;     if (l == 1) { const f32x2 g0 = *(const f32x2*)(P.hgrn_lb_logits + (size_t)(d * 2 + 0) * 512 + h * 128 + k), g1 = *(const f32x2*)(P.hgrn_lb_logits + (size_t)(d * 2 + 1) * 512 + h * 128 + k);
;         lb2.x = sigmoid_(g1.x - g0.x); lb2.y = sigmoid_(g1.y - g0.y); }
;     __syncthreads();
;     zero_operand_pads<128, 64>(OP, tid, 512);
;     f32x4 S[8];
; #pragma unroll
;     for (int i = 0; i < 8; ++i) S[i] = (f32x4){0.f, 0.f, 0.f, 0.f};
;     f32x2 pq[4], pf[4]; float pv[4] = {0.f, 0.f, 0.f, 0.f};
;     ...
;     HGM_LOAD(0);
.LBB0_159:
	s_or_b64 exec, exec, s[6:7]
	s_ashr_i32 s12, s11, 6
	s_and_b32 s21, s12, 3
	s_ashr_i32 s13, s11, 8
	s_ashr_i32 s6, s89, 4
	s_lshl_b32 s7, s13, 4
	s_lshl_b32 s8, s21, 2
	s_or_b32 s38, s8, s7
	s_lshl_b32 s39, s6, 8
	s_lshl_b32 s36, s6, 11
	s_addk_i32 s39, 0x2000
	s_or_b32 s8, s38, 2
	s_add_i32 s6, s38, 0xffffff02
	s_cmpk_lt_i32 s8, 0x100
	s_cselect_b32 s9, 0xff, s33
	s_cselect_b32 s11, s8, s6
	s_cselect_b32 s14, s39, s36
	s_or_b32 s6, s38, 3
	s_add_i32 s7, s38, 0xffffff03
	s_cmpk_lt_i32 s6, 0x100
	s_cselect_b32 s15, 0xff, s33
	s_cselect_b32 s16, s6, s7
	s_cselect_b32 s17, s39, s36
	s_sub_i32 s15, s15, s6
	s_cmp_eq_u32 s20, 0
	s_cselect_b64 s[6:7], -1, 0
	s_and_b64 s[6:7], s[6:7], exec
	s_cselect_b32 s16, s16, s15
	s_sub_i32 s8, s9, s8
	s_cmp_eq_u32 s20, 0
	s_cselect_b64 s[6:7], -1, 0
	s_and_b64 s[6:7], s[6:7], exec
	s_cselect_b32 s15, s11, s8
	s_or_b32 s6, s38, 1
	s_add_i32 s7, s38, 0xffffff01
	s_cmpk_lt_i32 s6, 0x100
	s_cselect_b32 s8, 0xff, s33
	s_cselect_b32 s9, s6, s7
	s_cselect_b32 s11, s39, s36
	s_sub_i32 s8, s8, s6
	s_cmp_eq_u32 s20, 0
	s_cselect_b64 s[6:7], -1, 0
	s_and_b64 s[6:7], s[6:7], exec
	s_cselect_b32 s18, s9, s8
	s_add_i32 s6, s38, 0xffffff00
	s_cmpk_lt_i32 s38, 0x100
	s_cselect_b32 s7, 0xff, s33
	s_cselect_b32 s19, s38, s6
	s_cselect_b32 s23, s39, s36
	s_sub_i32 s22, s7, s38
	s_cmp_eq_u32 s20, 0
	s_cselect_b64 s[6:7], -1, 0
	s_and_b64 s[8:9], s[6:7], exec
	s_cselect_b32 s8, s19, s22
	s_add_i32 s26, s8, s23
	s_lshl_b32 s22, s10, 7
	s_mul_i32 s9, s26, 0x1400
	v_readlane_b32 s42, v255, 35
	s_mul_hi_i32 s8, s26, 0x1400
	v_readlane_b32 s43, v255, 36
	s_add_u32 s24, s42, s9
	s_mul_i32 s23, s26, 0x2a00
	s_addc_u32 s27, s43, s8
	s_mul_hi_i32 s19, s26, 0x2a00
	s_add_u32 s8, s94, s23
	s_addc_u32 s9, s95, s19
	s_lshl_b32 s25, s10, 8
	s_add_u32 s8, s8, s25
	s_addc_u32 s9, s9, 0
	v_lshlrev_b32_e32 v8, 1, v2
	v_mov_b32_e32 v9, v3
	s_lshl_b32 s23, s20, 11
	v_lshl_add_u64 v[10:11], s[8:9], 0, v[8:9]
	s_add_u32 s8, s24, s23
	s_addc_u32 s9, s27, 0
	s_lshl_b32 s24, s10, 9
	s_add_u32 s8, s8, s24
	s_addc_u32 s9, s9, 0
	s_add_i32 s27, s18, s11
	s_mul_i32 s11, s27, 0x1400
	s_mul_hi_i32 s10, s27, 0x1400
	s_add_u32 s28, s42, s11
	s_mul_i32 s19, s27, 0x2a00
	s_addc_u32 s29, s43, s10
	s_mul_hi_i32 s18, s27, 0x2a00
	s_add_u32 s10, s94, s19
	s_addc_u32 s11, s95, s18
	s_add_u32 s10, s10, s25
	s_addc_u32 s11, s11, 0
	v_lshl_add_u64 v[12:13], s[10:11], 0, v[8:9]
	s_add_u32 s10, s28, s23
	s_addc_u32 s11, s29, 0
	s_add_u32 s10, s10, s24
	s_addc_u32 s11, s11, 0
	s_add_i32 s28, s15, s14
	s_mul_i32 s15, s28, 0x1400
	s_mul_hi_i32 s14, s28, 0x1400
	s_add_u32 s29, s42, s15
	s_mul_i32 s19, s28, 0x2a00
	s_addc_u32 s30, s43, s14
	s_mul_hi_i32 s18, s28, 0x2a00
	s_add_u32 s14, s94, s19
	s_addc_u32 s15, s95, s18
	s_add_u32 s14, s14, s25
	s_addc_u32 s15, s15, 0
	v_lshl_add_u64 v[14:15], s[14:15], 0, v[8:9]
	s_add_u32 s14, s29, s23
	s_addc_u32 s15, s30, 0
	s_add_u32 s14, s14, s24
	s_addc_u32 s15, s15, 0
	s_add_i32 s29, s16, s17
	s_mul_i32 s17, s29, 0x1400
	s_mul_hi_i32 s16, s29, 0x1400
	s_add_u32 s18, s42, s17
	s_addc_u32 s19, s43, s16
	s_mul_i32 s17, s29, 0x2a00
	s_mov_b32 s2, 0x26201000
	s_mul_hi_i32 s16, s29, 0x2a00
	s_add_u32 s17, s94, s17
	v_add_co_u32_e32 v10, vcc, s2, v10
	s_addc_u32 s30, s95, s16
	s_nop 0
	v_addc_co_u32_e32 v11, vcc, 0, v11, vcc
	s_add_u32 s16, s17, s25
	v_add_co_u32_e32 v12, vcc, s2, v12
	s_addc_u32 s17, s30, 0
	s_nop 0
	v_addc_co_u32_e32 v13, vcc, 0, v13, vcc
	v_lshl_add_u64 v[8:9], s[16:17], 0, v[8:9]
	s_add_u32 s16, s18, s23
	v_add_co_u32_e32 v14, vcc, s2, v14
	s_addc_u32 s17, s19, 0
	s_nop 0
	v_addc_co_u32_e32 v15, vcc, 0, v15, vcc
	s_add_u32 s16, s16, s24
	v_add_co_u32_e32 v8, vcc, s2, v8
	s_addc_u32 s17, s17, 0
	v_readlane_b32 s2, v255, 45
	s_add_u32 s18, s2, s25
	v_readlane_b32 s2, v255, 46
	s_addc_u32 s19, s2, 0
	s_lshl_b32 s30, s89, 7
	s_and_b32 s31, s30, 0x80
	s_add_u32 s18, s18, s31
	s_addc_u32 s19, s19, 0
	v_addc_co_u32_e32 v9, vcc, 0, v9, vcc
	v_lshl_add_u64 v[56:57], s[18:19], 0, v[2:3]
	global_load_dword v5, v[10:11], off offset:2048
	global_load_dword v16, v[12:13], off offset:2048
	s_nop 0
	global_load_dword v14, v[14:15], off offset:2048
	s_nop 0
	global_load_dword v15, v[8:9], off offset:2048
	v_mad_i64_i32 v[8:9], s[18:19], s26, v190, v[56:57]
	v_mad_i64_i32 v[10:11], s[18:19], s27, v190, v[56:57]
	v_mad_i64_i32 v[12:13], s[18:19], s29, v190, v[56:57]
	global_load_ushort v12, v[12:13], off
	s_nop 0
	global_load_ushort v13, v[8:9], off
	s_nop 0
	global_load_ushort v10, v[10:11], off
	v_mad_i64_i32 v[8:9], s[18:19], s28, v190, v[56:57]
	global_load_ushort v8, v[8:9], off
	s_nop 0
	global_load_dwordx2 v[66:67], v4, s[8:9] offset:64
	global_load_dwordx2 v[64:65], v4, s[10:11] offset:64
	global_load_dwordx2 v[62:63], v4, s[14:15] offset:64
	global_load_dwordx2 v[58:59], v4, s[16:17] offset:64
	s_lshl_b32 s8, s13, 11
	s_add_i32 s8, s8, 0
	s_lshl_b32 s9, s21, 9
	s_mulk_i32 s13, 0x7100
	s_add_i32 s9, s8, s9
	s_add_i32 s37, s13, 0
	s_cmp_lt_u32 s21, 2
	s_cselect_b64 s[26:27], -1, 0
	s_cmp_eq_u32 s21, 0
	s_cselect_b64 s[18:19], -1, 0
	s_cmp_eq_u32 s21, 3
	v_lshrrev_b32_e32 v9, 4, v7
	s_cselect_b64 s[16:17], -1, 0
	s_movk_i32 s2, 0xa0
	s_lshl_b32 s34, s21, 3
	v_and_b32_e32 v116, 15, v6
	s_cmp_lt_i32 s12, 4
	s_waitcnt vmcnt(0)
; __device__ __forceinline__ float sigmoid_(float x) { return __builtin_amdgcn_rcpf(1.f + __expf(-x)); }
; __device__ __forceinline__ void scan_hgrn_mfma(const Params& P, unsigned char* LB, int l, int c) {
;     ...
;     const int k = 2 * lane, qt = wave & 3, cb = wave >> 2;
;     const int vv_ = tid & 63, vqt = wave & 3, vc = wave >> 2;
;     f32x2 lb2 = {0.f, 0.f};
;     if (l == 1) { const f32x2 g0 = *(const f32x2*)(P.hgrn_lb_logits + (size_t)(d * 2 + 0) * 512 + h * 128 + k), g1 = *(const f32x2*)(P.hgrn_lb_logits + (size_t)(d * 2 + 1) * 512 + h * 128 + k);
;         lb2.x = sigmoid_(g1.x - g0.x); lb2.y = sigmoid_(g1.y - g0.y); }
;     __syncthreads();
;     zero_operand_pads<128, 64>(OP, tid, 512);
;     f32x4 S[8];
; #pragma unroll
;     for (int i = 0; i < 8; ++i) S[i] = (f32x4){0.f, 0.f, 0.f, 0.f};
;     f32x2 pq[4], pf[4]; float pv[4] = {0.f, 0.f, 0.f, 0.f};
;     ...
;     HGM_LOAD(0);
	v_and_b32_e32 v119, 48, v6
	v_lshlrev_b32_e32 v6, 2, v9
	v_add_u32_e32 v125, s9, v4
	v_add_u32_e32 v124, s8, v4
	s_cselect_b64 s[28:29], -1, 0
	v_lshlrev_b32_e32 v121, 3, v7
	s_lshl_b32 s30, s12, 4
	v_cmp_gt_u32_e64 s[14:15], v6, v116
	v_cmp_lt_u32_e64 s[8:9], v6, v116
	s_mulk_i32 s20, 0x2400
	s_add_i32 s58, s20, 0x9000
	v_lshlrev_b32_e32 v52, 3, v9
	v_mov_b32_e32 v53, v3
	v_mov_b32_e32 v32, 0
	s_mov_b32 s40, 0
	v_pk_add_f32 v[54:55], v[0:1], 1.0 op_sel_hi:[1,0] neg_lo:[1,0] neg_hi:[1,0]
	v_mul_u32_u24_e32 v118, 0x50, v116
	v_add_u32_e32 v117, 0, v119
	v_sub_u32_e32 v126, 0, v116
	v_lshlrev_b32_e32 v2, 1, v2
	s_mov_b32 s44, 0
	v_mov_b32_e32 v33, v32
	v_mov_b32_e32 v34, v32
	v_mov_b32_e32 v35, v32
	v_mov_b32_e32 v28, v32
	v_mov_b32_e32 v29, v32
	v_mov_b32_e32 v30, v32
	v_mov_b32_e32 v31, v32
	v_mov_b32_e32 v24, v32
	v_mov_b32_e32 v25, v32
	v_mov_b32_e32 v26, v32
	v_mov_b32_e32 v27, v32
	v_mov_b32_e32 v20, v32
	v_mov_b32_e32 v21, v32
	v_mov_b32_e32 v22, v32
	v_mov_b32_e32 v23, v32
	v_mov_b32_e32 v17, v32
	v_mov_b32_e32 v18, v32
	v_mov_b32_e32 v19, v32
	v_mov_b32_e32 v9, v32
	s_waitcnt vmcnt(11)
	v_lshlrev_b32_e32 v70, 16, v5
	v_and_b32_e32 v71, 0xffff0000, v5
	v_mov_b32_e32 v5, v3
	s_waitcnt vmcnt(10)
	v_lshlrev_b32_e32 v68, 16, v16
	v_and_b32_e32 v69, 0xffff0000, v16
	s_waitcnt vmcnt(9)
	v_lshlrev_b32_e32 v50, 16, v14
	v_and_b32_e32 v51, 0xffff0000, v14
	s_waitcnt vmcnt(8)
	v_lshlrev_b32_e32 v48, 16, v15
	v_and_b32_e32 v49, 0xffff0000, v15
	s_waitcnt vmcnt(6)
	v_lshlrev_b32_e32 v44, 16, v13
	s_waitcnt vmcnt(5)
	v_lshlrev_b32_e32 v45, 16, v10
	v_lshl_add_u32 v10, v7, 2, s37
	v_lshlrev_b32_e32 v47, 16, v12
	s_waitcnt vmcnt(4)
	v_lshlrev_b32_e32 v46, 16, v8
	v_mov_b32_e32 v8, s37
	v_mad_u32_u24 v11, v7, s2, v8
	s_movk_i32 s2, 0x50
	v_mad_u32_u24 v8, v7, s2, v8
	v_or_b32_e32 v7, 2, v6
	v_or_b32_e32 v6, 3, v6
	v_cmp_gt_u32_e64 s[12:13], v6, v116
	v_or_b32_e32 v6, s30, v116
	v_mul_lo_u32 v6, v6, s2
	v_readlane_b32 s2, v255, 32
	s_add_u32 s20, s2, s25
	v_readlane_b32 s2, v255, 33
	s_addc_u32 s25, s2, 0
	s_add_u32 s20, s20, s31
	s_addc_u32 s25, s25, 0
	s_ashr_i32 s31, s30, 31
	s_lshl_b64 s[30:31], s[30:31], 1
	s_add_u32 s30, s20, s30
	s_addc_u32 s31, s25, s31
	s_add_u32 s20, s42, s23
	s_mul_i32 s25, s21, 0x440
	s_addc_u32 s21, s43, 0
	s_add_u32 s20, s20, s24
	s_movk_i32 s2, 0x110
	s_addc_u32 s21, s21, 0
	v_cmp_gt_u32_e64 s[10:11], v7, v116
	v_lshl_add_u64 v[76:77], s[30:31], 0, v[52:53]
	v_mad_u32_u24 v53, v116, s2, 0
	v_add_u32_e32 v120, 0, v6
	v_lshl_add_u64 v[60:61], s[20:21], 0, v[4:5]
	s_sub_i32 s41, 0, s38
	s_lshl_b32 s42, s22, 1
	v_add_u32_e32 v123, s25, v10
	v_add_u32_e32 v127, s34, v11
	v_add_u32_e32 v122, s34, v8
	s_mov_b32 s43, 0
	v_mov_b32_e32 v16, v32
	v_mov_b32_e32 v12, v32
	v_mov_b32_e32 v13, v32
	v_mov_b32_e32 v14, v32
	v_mov_b32_e32 v15, v32
	v_mov_b32_e32 v8, v32
	v_mov_b32_e32 v10, v32
	v_mov_b32_e32 v11, v32
	v_mov_b32_e32 v4, v32
	v_mov_b32_e32 v5, v32
	v_mov_b32_e32 v6, v32
	v_mov_b32_e32 v7, v32
	s_waitcnt vmcnt(0)
	s_and_b64 s[50:51], s[6:7], exec
	s_cselect_b32 s46, 1, -1
	s_mul_i32 s47, s46, 0x2a00
	s_ashr_i32 s48, s46, 31
	s_branch .LBB0_162

; __device__ __forceinline__ void scan_hgrn_mfma(const Params& P, unsigned char* LB, int l, int c) {
;     ...
;         { f32x2 fc[4];
; #pragma unroll
;           for (int r = 0; r < 4; ++r) {
;               const float eq0 = 1.f + __expf(fminf(-pq[r].x, 40.f)), ef0 = 1.f + __expf(fminf(-pf[r].x, 40.f)), r0_ = __builtin_amdgcn_rcpf(eq0 * ef0);
;               const float eq1 = 1.f + __expf(fminf(-pq[r].y, 40.f)), ef1 = 1.f + __expf(fminf(-pf[r].y, 40.f)), r1_ = __builtin_amdgcn_rcpf(eq1 * ef1);
;               q[r].x = pq[r].x * (ef0 * r0_) * 0.08838834764831845f; q[r].y = pq[r].y * (ef1 * r1_) * 0.08838834764831845f;
;               const float f0 = lb2.x + (1.f - lb2.x) * (eq0 * r0_), f1 = lb2.y + (1.f - lb2.y) * (eq1 * r1_);
;               kk[r].x = 1.f - f0; kk[r].y = 1.f - f1; fc[r].x = fmaxf(f0, 1e-4f); fc[r].y = fmaxf(f1, 1e-4f); vv[r] = pv[r];
;           }
;           pre[0] = fc[0]; pre[1] = pre[0] * fc[1]; pre[2] = pre[1] * fc[2]; pre[3] = pre[2] * fc[3];
;           suf[3] = (f32x2){1.f, 1.f}; suf[2] = fc[3]; suf[1] = suf[2] * fc[2]; suf[0] = suf[1] * fc[1]; }
;         *(f32x2*)&tot[(cb * 4 + qt) * 128 + k] = pre[3];
;         __syncthreads();
;         if (tile + 1 < NTILES) HGM_LOAD(tile + 1);
.LBB0_162:
	v_max_f32_e64 v37, -v66, -v66
	v_min_f32_e32 v37, 0x42200000, v37
	v_mul_f32_e32 v37, 0x3fb8aa3b, v37
	v_max_f32_e64 v36, -v70, -v70
	v_exp_f32_e32 v38, v37
	v_max_f32_e64 v37, -v71, -v71
	v_max_f32_e64 v39, -v67, -v67
	v_min_f32_e32 v36, 0x42200000, v36
	v_min_f32_e32 v37, 0x42200000, v37
	v_min_f32_e32 v39, 0x42200000, v39
	v_mul_f32_e32 v36, 0x3fb8aa3b, v36
	v_mul_f32_e32 v37, 0x3fb8aa3b, v37
	v_mul_f32_e32 v39, 0x3fb8aa3b, v39
	v_exp_f32_e32 v36, v36
	v_exp_f32_e32 v39, v39
	v_exp_f32_e32 v37, v37
	v_max_f32_e64 v41, -v65, -v65
	v_min_f32_e32 v41, 0x42200000, v41
	v_pk_add_f32 v[94:95], v[38:39], 1.0 op_sel_hi:[1,0]
	v_pk_add_f32 v[36:37], v[36:37], 1.0 op_sel_hi:[1,0]
	v_mul_f32_e32 v41, 0x3fb8aa3b, v41
	v_pk_mul_f32 v[38:39], v[36:37], v[94:95]
	v_exp_f32_e32 v41, v41
	v_rcp_f32_e32 v99, v39
	v_max_f32_e64 v39, -v64, -v64
	v_min_f32_e32 v39, 0x42200000, v39
	v_mul_f32_e32 v39, 0x3fb8aa3b, v39
	v_rcp_f32_e32 v98, v38
	v_max_f32_e64 v38, -v68, -v68
	v_exp_f32_e32 v40, v39
	v_max_f32_e64 v39, -v69, -v69
	v_min_f32_e32 v38, 0x42200000, v38
	v_min_f32_e32 v39, 0x42200000, v39
	v_mul_f32_e32 v38, 0x3fb8aa3b, v38
	v_mul_f32_e32 v39, 0x3fb8aa3b, v39
	v_exp_f32_e32 v38, v38
	v_exp_f32_e32 v39, v39
	v_pk_add_f32 v[86:87], v[40:41], 1.0 op_sel_hi:[1,0]
	v_pk_mul_f32 v[36:37], v[36:37], v[98:99]
	s_add_i32 s22, s38, s43
	v_pk_add_f32 v[38:39], v[38:39], 1.0 op_sel_hi:[1,0]
	v_pk_fma_f32 v[102:103], v[54:55], v[36:37], v[0:1]
	v_pk_mul_f32 v[40:41], v[38:39], v[86:87]
	s_add_i32 s20, s22, 32
	v_rcp_f32_e32 v88, v40
	v_rcp_f32_e32 v89, v41
	v_max_f32_e64 v41, -v63, -v63
	v_min_f32_e32 v41, 0x42200000, v41
	v_mul_f32_e32 v41, 0x3fb8aa3b, v41
	v_pk_mul_f32 v[36:37], v[38:39], v[88:89]
	v_max_f32_e64 v39, -v62, -v62
	v_min_f32_e32 v39, 0x42200000, v39
	v_mul_f32_e32 v39, 0x3fb8aa3b, v39
	v_max_f32_e64 v38, -v50, -v50
	v_exp_f32_e32 v40, v39
	v_max_f32_e64 v39, -v51, -v51
	v_min_f32_e32 v38, 0x42200000, v38
	v_min_f32_e32 v39, 0x42200000, v39
	v_mul_f32_e32 v38, 0x3fb8aa3b, v38
	v_mul_f32_e32 v39, 0x3fb8aa3b, v39
	v_exp_f32_e32 v38, v38
	v_exp_f32_e32 v41, v41
	v_exp_f32_e32 v39, v39
	v_pk_fma_f32 v[92:93], v[54:55], v[36:37], v[0:1]
	s_add_i32 s21, s22, 0xffffff20
	v_pk_add_f32 v[80:81], v[40:41], 1.0 op_sel_hi:[1,0]
	v_pk_add_f32 v[36:37], v[38:39], 1.0 op_sel_hi:[1,0]
	v_max_f32_e64 v41, -v59, -v59
	v_pk_mul_f32 v[38:39], v[36:37], v[80:81]
	v_min_f32_e32 v41, 0x42200000, v41
	v_rcp_f32_e32 v85, v39
	v_max_f32_e64 v39, -v58, -v58
	v_min_f32_e32 v39, 0x42200000, v39
	v_mul_f32_e32 v39, 0x3fb8aa3b, v39
	v_rcp_f32_e32 v84, v38
	v_max_f32_e64 v38, -v48, -v48
	v_exp_f32_e32 v40, v39
	v_max_f32_e64 v39, -v49, -v49
	v_min_f32_e32 v38, 0x42200000, v38
	v_min_f32_e32 v39, 0x42200000, v39
	s_cmpk_lt_i32 s20, 0x100
	v_mul_f32_e32 v38, 0x3fb8aa3b, v38
	v_mul_f32_e32 v39, 0x3fb8aa3b, v39
	v_mul_f32_e32 v41, 0x3fb8aa3b, v41
	s_cselect_b32 s23, 0xff, s33
	v_exp_f32_e32 v38, v38
	v_exp_f32_e32 v41, v41
	v_exp_f32_e32 v39, v39
	s_cselect_b32 s24, s20, s21
	s_cselect_b32 s25, s39, s36
	s_add_i32 s20, s41, s23
	s_add_i32 s20, s20, s40
	s_sub_i32 s23, s20, 32
	s_and_b64 s[20:21], s[6:7], exec
	v_pk_add_f32 v[72:73], v[40:41], 1.0 op_sel_hi:[1,0]
	v_pk_add_f32 v[38:39], v[38:39], 1.0 op_sel_hi:[1,0]
	s_cselect_b32 s20, s24, s23
	v_pk_mul_f32 v[40:41], v[38:39], v[72:73]
	s_add_i32 s23, s20, s25
	v_rcp_f32_e32 v74, v40
	v_rcp_f32_e32 v75, v41
	s_mul_i32 s21, s23, 0x2a00
	s_mul_hi_i32 s20, s23, 0x2a00
	s_add_u32 s21, s94, s21
	s_addc_u32 s24, s95, s20
	s_add_u32 s20, s21, s42
	v_pk_mul_f32 v[38:39], v[38:39], v[74:75]
	s_addc_u32 s21, s24, 0
	s_mov_b64 s[50:51], s[20:21]
	v_pk_fma_f32 v[78:79], v[54:55], v[38:39], v[0:1]
	v_lshl_add_u64 v[38:39], s[20:21], 0, v[2:3]
	v_mad_i64_i32 v[40:41], s[20:21], s23, v191, v[60:61]
	s_add_u32 s50, s50, s47
	s_addc_u32 s51, s51, s48
	s_add_i32 s24, s23, s46
	v_lshl_add_u64 v[42:43], s[50:51], 0, v[2:3]
	v_mad_i64_i32 v[58:59], s[20:21], s24, v191, v[60:61]
	v_pk_mul_f32 v[36:37], v[36:37], v[84:85]
	v_max_f32_e32 v106, 0x38d1b717, v102
	v_max_f32_e32 v107, 0x38d1b717, v103
	v_max_f32_e32 v110, 0x38d1b717, v92
	v_max_f32_e32 v111, 0x38d1b717, v93
	v_pk_fma_f32 v[90:91], v[54:55], v[36:37], v[0:1]
	s_mov_b32 s2, 0x26201000
	v_max_f32_e32 v36, 0x38d1b717, v90
	v_max_f32_e32 v37, 0x38d1b717, v91
	v_pk_mul_f32 v[108:109], v[110:111], v[106:107]
	v_add_co_u32_e32 v38, vcc, s2, v38
	v_max_f32_e32 v100, 0x38d1b717, v78
	v_max_f32_e32 v101, 0x38d1b717, v79
	v_pk_mul_f32 v[96:97], v[36:37], v[108:109]
	v_addc_co_u32_e32 v39, vcc, 0, v39, vcc
	v_pk_mul_f32 v[82:83], v[100:101], v[96:97]
	v_add_co_u32_e32 v42, vcc, s2, v42
	s_add_u32 s50, s50, s47
	s_addc_u32 s51, s51, s48
	s_add_i32 s25, s24, s46
	s_mov_b64 s[20:21], s[50:51]
	ds_write_b64 v125, v[82:83] offset:58368
	s_waitcnt lgkmcnt(0)
	s_barrier
	v_addc_co_u32_e32 v43, vcc, 0, v43, vcc
	global_load_dword v128, v[38:39], off offset:2048
	global_load_dwordx2 v[66:67], v[40:41], off offset:64
	global_load_dword v129, v[42:43], off offset:2048
	global_load_dwordx2 v[64:65], v[58:59], off offset:64
	v_lshl_add_u64 v[38:39], s[20:21], 0, v[2:3]
	v_mad_i64_i32 v[40:41], s[20:21], s25, v191, v[60:61]
	v_add_co_u32_e32 v38, vcc, s2, v38
	s_nop 1
	v_addc_co_u32_e32 v39, vcc, 0, v39, vcc
	s_add_u32 s50, s50, s47
	s_addc_u32 s51, s51, s48
	s_add_i32 s22, s25, s46
	v_lshl_add_u64 v[42:43], s[50:51], 0, v[2:3]
	v_add_co_u32_e32 v42, vcc, s2, v42
	v_mad_i64_i32 v[58:59], s[20:21], s22, v191, v[60:61]
	s_nop 0
	v_addc_co_u32_e32 v43, vcc, 0, v43, vcc
	global_load_dword v131, v[38:39], off offset:2048
	global_load_dwordx2 v[62:63], v[40:41], off offset:64
	global_load_dword v132, v[42:43], off offset:2048
	s_nop 0
	global_load_dwordx2 v[58:59], v[58:59], off offset:64
	v_mad_i64_i32 v[38:39], s[20:21], s23, v190, v[56:57]
	v_mad_i64_i32 v[40:41], s[20:21], s24, v190, v[56:57]
	v_mad_i64_i32 v[42:43], s[20:21], s25, v190, v[56:57]
	v_mad_i64_i32 v[104:105], s[20:21], s22, v190, v[56:57]
	global_load_ushort v136, v[38:39], off
	global_load_ushort v137, v[40:41], off
	global_load_ushort v130, v[42:43], off
	global_load_ushort v135, v[104:105], off
	v_pk_mul_f32 v[112:113], v[100:101], v[36:37]
	ds_read2st64_b64 v[40:43], v124 offset0:114 offset1:115
	ds_read2st64_b64 v[36:39], v124 offset0:116 offset1:117
	s_mov_b64 s[20:21], -1
	s_and_b64 vcc, exec, s[26:27]
	s_cbranch_vccz .LBB0_164
	v_pk_mul_f32 v[104:105], v[110:111], v[112:113]
	s_mov_b64 s[20:21], 0
	s_waitcnt lgkmcnt(1)
	v_pk_mul_f32 v[110:111], v[104:105], v[42:43]
	s_nop 0
	v_cndmask_b32_e64 v105, v105, v111, s[18:19]
	v_cndmask_b32_e64 v104, v104, v110, s[18:19]
	v_rcp_f32_e32 v114, v104
	v_rcp_f32_e32 v115, v105
